# barrier spin-wait tightening: v92 minus the s_sleep in the 11 grid-barrier poll loops
# baseline (speedup 1.0000x reference)
.Lh2_spin_0:
	global_load_dword v4, v2, s[100:101] sc1
	s_waitcnt vmcnt(0)
	v_cmp_lt_u32_e32 vcc, v4, v9
	s_cbranch_vccnz .Lh2_spin_0
	buffer_inv sc1
	s_waitcnt vmcnt(0)

.Lh2_spin_5:
	global_load_dword v4, v2, s[100:101] sc1
	s_waitcnt vmcnt(0)
	v_cmp_lt_u32_e32 vcc, v4, v9
	s_cbranch_vccnz .Lh2_spin_5
	buffer_inv sc1
	s_waitcnt vmcnt(0)
	s_branch .LBB0_380

.Lf2_spin_b:
	global_load_dword v234, v232, s[100:101] sc1
	s_waitcnt vmcnt(0)
	v_cmp_lt_u32_e32 vcc, v234, v239
	s_cbranch_vccnz .Lf2_spin_b
	buffer_inv sc1
	s_waitcnt vmcnt(0)
